# v007 + attention B row-max with v_max3 tree after the bias FMAs and permlane32_swap cross-half max
# speedup vs baseline: 1.0178x; 1.0026x over previous
.LBB0_397:
	s_add_i32 s43, s38, -3
	s_cmp_lt_u32 s43, s36
	s_cselect_b64 s[12:13], -1, 0
	s_cmp_gt_i32 s43, s35
	s_cselect_b64 s[44:45], -1, 0
	s_or_b64 s[12:13], s[12:13], s[44:45]
	s_and_b64 vcc, exec, s[12:13]
	s_cbranch_vccnz .LBB0_401
	s_and_b32 s12, s37, 0xc000
	s_add_i32 s12, s12, 0
	v_add_u32_e32 v88, s12, v174
	v_add_u32_e32 v36, v88, v173
	ds_read_b128 v[32:35], v36
	ds_read_b128 v[48:51], v36 offset:4096
	v_add_u32_e32 v84, v88, v177
	ds_read_b128 v[80:83], v84
	ds_read_b128 v[84:87], v84 offset:4096
	v_add_u32_e32 v89, v88, v179
	s_waitcnt lgkmcnt(0)
	v_mfma_f32_32x32x16_bf16 v[32:47], v[32:35], v[64:67], 0
	v_add_u32_e32 v88, v88, v180
	v_mfma_f32_32x32x16_bf16 v[48:63], v[48:51], v[64:67], 0
	v_mfma_f32_32x32x16_bf16 v[32:47], v[80:83], v[68:71], v[32:47]
	v_mfma_f32_32x32x16_bf16 v[48:63], v[84:87], v[68:71], v[48:63]
	ds_read_b128 v[80:83], v89
	ds_read_b128 v[84:87], v89 offset:4096
	s_waitcnt lgkmcnt(0)
	v_mfma_f32_32x32x16_bf16 v[32:47], v[80:83], v[72:75], v[32:47]
	ds_read_b128 v[80:83], v88
	ds_read_b128 v[120:123], v88 offset:4096
	v_mfma_f32_32x32x16_bf16 v[48:63], v[84:87], v[72:75], v[48:63]
	v_and_b32_e32 v84, -16, v118
	v_add_u32_e32 v124, v117, v84
	s_waitcnt lgkmcnt(0)
	v_mfma_f32_32x32x16_bf16 v[32:47], v[80:83], v[76:79], v[32:47]
	ds_read_b128 v[90:93], v124
	ds_read_b128 v[82:85], v124 offset:32
	ds_read_b128 v[94:97], v124 offset:128
	ds_read_b128 v[86:89], v124 offset:160
	v_mfma_f32_32x32x16_bf16 v[48:63], v[120:123], v[76:79], v[48:63]
	s_waitcnt lgkmcnt(0)
	s_nop 5
	v_fmamk_f32 v98, v32, 0x3e38aa3b, v90
	v_fmamk_f32 v121, v33, 0x3e38aa3b, v91
	v_fmac_f32_e32 v93, 0x3e38aa3b, v35
	v_fmamk_f32 v90, v37, 0x3e38aa3b, v83
	v_fmac_f32_e32 v85, 0x3e38aa3b, v39
	v_fmamk_f32 v122, v48, 0x3e38aa3b, v94
	v_fmamk_f32 v120, v49, 0x3e38aa3b, v95
	v_fmamk_f32 v95, v34, 0x3e38aa3b, v92
	v_fmamk_f32 v94, v50, 0x3e38aa3b, v96
	v_fmac_f32_e32 v97, 0x3e38aa3b, v51
	v_fmamk_f32 v92, v36, 0x3e38aa3b, v82
	v_fmamk_f32 v91, v52, 0x3e38aa3b, v86
	v_fmamk_f32 v86, v53, 0x3e38aa3b, v87
	v_fmamk_f32 v53, v38, 0x3e38aa3b, v84
	ds_read_b128 v[48:51], v124 offset:64
	ds_read_b128 v[36:39], v124 offset:96
	ds_read_b128 v[80:83], v124 offset:192
	ds_read_b128 v[32:35], v124 offset:224
	v_fmamk_f32 v52, v54, 0x3e38aa3b, v88
	s_waitcnt lgkmcnt(0)
	v_fmamk_f32 v54, v40, 0x3e38aa3b, v48
	v_fmamk_f32 v40, v44, 0x3e38aa3b, v36
	v_fmac_f32_e32 v51, 0x3e38aa3b, v43
	v_fmamk_f32 v36, v60, 0x3e38aa3b, v32
	v_fmamk_f32 v32, v62, 0x3e38aa3b, v34
	v_fmac_f32_e32 v89, 0x3e38aa3b, v55
	v_fmamk_f32 v55, v56, 0x3e38aa3b, v80
	v_fmamk_f32 v49, v41, 0x3e38aa3b, v49
	v_fmamk_f32 v48, v57, 0x3e38aa3b, v81
	v_fmamk_f32 v42, v42, 0x3e38aa3b, v50
	v_fmamk_f32 v41, v58, 0x3e38aa3b, v82
	v_fmac_f32_e32 v83, 0x3e38aa3b, v59
	v_fmamk_f32 v37, v45, 0x3e38aa3b, v37
	v_fmamk_f32 v33, v61, 0x3e38aa3b, v33
	v_fmamk_f32 v38, v46, 0x3e38aa3b, v38
	v_fmac_f32_e32 v39, 0x3e38aa3b, v47
	v_fmac_f32_e32 v35, 0x3e38aa3b, v63
	v_max3_f32 v34, v98, v121, v95
	v_max3_f32 v43, v93, v92, v90
	v_max3_f32 v44, v53, v85, v54
	v_max3_f32 v45, v49, v42, v51
	v_max3_f32 v34, v34, v40, v37
	v_max3_f32 v43, v43, v38, v39
	v_max3_f32 v44, v44, v122, v120
	v_max3_f32 v45, v45, v94, v97
	v_max3_f32 v34, v34, v91, v86
	v_max3_f32 v43, v43, v52, v89
	v_max3_f32 v44, v44, v55, v48
	v_max3_f32 v45, v45, v41, v83
	v_max3_f32 v34, v34, v36, v33
	v_max3_f32 v43, v43, v32, v35
	v_max3_f32 v34, v34, v43, v44
	v_max_f32_e32 v34, v34, v45
	v_mov_b32_e32 v43, v34
	v_mov_b32_e32 v44, v34
	s_nop 1
	v_permlane32_swap_b32_e32 v43, v44
	v_max_f32_e32 v34, v43, v44
	v_add_f32_e32 v43, 0x41000000, v119
	v_cmp_gt_f32_e32 vcc, v34, v43
	s_cbranch_vccz .LBB0_400
	v_max_f32_e32 v34, v34, v34
	v_max_f32_e32 v43, v119, v119
	v_max_f32_e32 v43, v43, v34
	v_sub_f32_e32 v34, v119, v43
	v_exp_f32_e32 v34, v34
	v_mov_b32_e32 v119, v43
	v_pk_mul_f32 v[14:15], v[14:15], v[34:35] op_sel_hi:[1,0]
	v_pk_mul_f32 v[12:13], v[12:13], v[34:35] op_sel_hi:[1,0]
	v_pk_mul_f32 v[10:11], v[10:11], v[34:35] op_sel_hi:[1,0]
	v_pk_mul_f32 v[8:9], v[8:9], v[34:35] op_sel_hi:[1,0]
	v_pk_mul_f32 v[6:7], v[6:7], v[34:35] op_sel_hi:[1,0]
	v_pk_mul_f32 v[4:5], v[4:5], v[34:35] op_sel_hi:[1,0]
	v_pk_mul_f32 v[2:3], v[2:3], v[34:35] op_sel_hi:[1,0]
	v_pk_mul_f32 v[0:1], v[0:1], v[34:35] op_sel_hi:[1,0]
	v_pk_mul_f32 v[30:31], v[30:31], v[34:35] op_sel_hi:[1,0]
	v_pk_mul_f32 v[28:29], v[28:29], v[34:35] op_sel_hi:[1,0]
	v_pk_mul_f32 v[26:27], v[26:27], v[34:35] op_sel_hi:[1,0]
	v_pk_mul_f32 v[24:25], v[24:25], v[34:35] op_sel_hi:[1,0]
	v_pk_mul_f32 v[22:23], v[22:23], v[34:35] op_sel_hi:[1,0]
	v_pk_mul_f32 v[20:21], v[20:21], v[34:35] op_sel_hi:[1,0]
	v_pk_mul_f32 v[18:19], v[18:19], v[34:35] op_sel_hi:[1,0]
	v_pk_mul_f32 v[16:17], v[16:17], v[34:35] op_sel_hi:[1,0]
	v_mul_f32_e32 v101, v101, v34
